# GEMM tile heads: 128 v_mov_b32 accumulator zeroing -> 64 v_mov_b64 (8 GEMM instances)
# speedup vs baseline: 1.0039x; 1.0014x over previous
.LBB0_143:
	ds_read_b128 v[148:151], v213 offset:32768
	ds_read_b128 v[144:147], v213 offset:36864
	ds_read_b128 v[140:143], v213 offset:40960
	ds_read_b128 v[136:139], v213 offset:45056
	ds_read_b128 v[132:135], v214
	ds_read_b128 v[128:131], v214 offset:4096
	s_mov_b32 s22, s46
	s_mov_b32 s58, s55
	s_mov_b32 s46, -2
	v_mov_b64_e32 v[0:1], 0
	v_mov_b64_e32 v[2:3], 0
	v_mov_b64_e32 v[4:5], 0
	v_mov_b64_e32 v[6:7], 0
	v_mov_b64_e32 v[8:9], 0
	v_mov_b64_e32 v[10:11], 0
	v_mov_b64_e32 v[12:13], 0
	v_mov_b64_e32 v[14:15], 0
	v_mov_b64_e32 v[16:17], 0
	v_mov_b64_e32 v[18:19], 0
	v_mov_b64_e32 v[20:21], 0
	v_mov_b64_e32 v[22:23], 0
	v_mov_b64_e32 v[24:25], 0
	v_mov_b64_e32 v[26:27], 0
	v_mov_b64_e32 v[28:29], 0
	v_mov_b64_e32 v[30:31], 0
	v_mov_b64_e32 v[32:33], 0
	v_mov_b64_e32 v[34:35], 0
	v_mov_b64_e32 v[36:37], 0
	v_mov_b64_e32 v[38:39], 0
	v_mov_b64_e32 v[40:41], 0
	v_mov_b64_e32 v[42:43], 0
	v_mov_b64_e32 v[44:45], 0
	v_mov_b64_e32 v[46:47], 0
	v_mov_b64_e32 v[48:49], 0
	v_mov_b64_e32 v[50:51], 0
	v_mov_b64_e32 v[52:53], 0
	v_mov_b64_e32 v[54:55], 0
	v_mov_b64_e32 v[56:57], 0
	v_mov_b64_e32 v[58:59], 0
	v_mov_b64_e32 v[60:61], 0
	v_mov_b64_e32 v[62:63], 0
	v_mov_b64_e32 v[64:65], 0
	v_mov_b64_e32 v[66:67], 0
	v_mov_b64_e32 v[68:69], 0
	v_mov_b64_e32 v[70:71], 0
	v_mov_b64_e32 v[72:73], 0
	v_mov_b64_e32 v[74:75], 0
	v_mov_b64_e32 v[76:77], 0
	v_mov_b64_e32 v[78:79], 0
	v_mov_b64_e32 v[80:81], 0
	v_mov_b64_e32 v[82:83], 0
	v_mov_b64_e32 v[84:85], 0
	v_mov_b64_e32 v[86:87], 0
	v_mov_b64_e32 v[88:89], 0
	v_mov_b64_e32 v[90:91], 0
	v_mov_b64_e32 v[92:93], 0
	v_mov_b64_e32 v[94:95], 0
	v_mov_b64_e32 v[96:97], 0
	v_mov_b64_e32 v[98:99], 0
	v_mov_b64_e32 v[100:101], 0
	v_mov_b64_e32 v[102:103], 0
	v_mov_b64_e32 v[104:105], 0
	v_mov_b64_e32 v[106:107], 0
	v_mov_b64_e32 v[108:109], 0
	v_mov_b64_e32 v[110:111], 0
	v_mov_b64_e32 v[112:113], 0
	v_mov_b64_e32 v[114:115], 0
	v_mov_b64_e32 v[116:117], 0
	v_mov_b64_e32 v[118:119], 0
	v_mov_b64_e32 v[120:121], 0
	v_mov_b64_e32 v[122:123], 0
	v_mov_b64_e32 v[124:125], 0
	v_mov_b64_e32 v[126:127], 0
	s_branch .LBB0_147

.LBB0_379:
	ds_read_b128 v[148:151], v205 offset:32768
	ds_read_b128 v[144:147], v205 offset:36864
	ds_read_b128 v[140:143], v205 offset:40960
	ds_read_b128 v[136:139], v205 offset:45056
	ds_read_b128 v[132:135], v206
	ds_read_b128 v[128:131], v206 offset:4096
	s_mov_b32 s62, s33
	s_mov_b32 s24, s61
	s_mov_b32 s33, -2
	v_mov_b64_e32 v[0:1], 0
	v_mov_b64_e32 v[2:3], 0
	v_mov_b64_e32 v[4:5], 0
	v_mov_b64_e32 v[6:7], 0
	v_mov_b64_e32 v[8:9], 0
	v_mov_b64_e32 v[10:11], 0
	v_mov_b64_e32 v[12:13], 0
	v_mov_b64_e32 v[14:15], 0
	v_mov_b64_e32 v[16:17], 0
	v_mov_b64_e32 v[18:19], 0
	v_mov_b64_e32 v[20:21], 0
	v_mov_b64_e32 v[22:23], 0
	v_mov_b64_e32 v[24:25], 0
	v_mov_b64_e32 v[26:27], 0
	v_mov_b64_e32 v[28:29], 0
	v_mov_b64_e32 v[30:31], 0
	v_mov_b64_e32 v[32:33], 0
	v_mov_b64_e32 v[34:35], 0
	v_mov_b64_e32 v[36:37], 0
	v_mov_b64_e32 v[38:39], 0
	v_mov_b64_e32 v[40:41], 0
	v_mov_b64_e32 v[42:43], 0
	v_mov_b64_e32 v[44:45], 0
	v_mov_b64_e32 v[46:47], 0
	v_mov_b64_e32 v[48:49], 0
	v_mov_b64_e32 v[50:51], 0
	v_mov_b64_e32 v[52:53], 0
	v_mov_b64_e32 v[54:55], 0
	v_mov_b64_e32 v[56:57], 0
	v_mov_b64_e32 v[58:59], 0
	v_mov_b64_e32 v[60:61], 0
	v_mov_b64_e32 v[62:63], 0
	v_mov_b64_e32 v[64:65], 0
	v_mov_b64_e32 v[66:67], 0
	v_mov_b64_e32 v[68:69], 0
	v_mov_b64_e32 v[70:71], 0
	v_mov_b64_e32 v[72:73], 0
	v_mov_b64_e32 v[74:75], 0
	v_mov_b64_e32 v[76:77], 0
	v_mov_b64_e32 v[78:79], 0
	v_mov_b64_e32 v[80:81], 0
	v_mov_b64_e32 v[82:83], 0
	v_mov_b64_e32 v[84:85], 0
	v_mov_b64_e32 v[86:87], 0
	v_mov_b64_e32 v[88:89], 0
	v_mov_b64_e32 v[90:91], 0
	v_mov_b64_e32 v[92:93], 0
	v_mov_b64_e32 v[94:95], 0
	v_mov_b64_e32 v[96:97], 0
	v_mov_b64_e32 v[98:99], 0
	v_mov_b64_e32 v[100:101], 0
	v_mov_b64_e32 v[102:103], 0
	v_mov_b64_e32 v[104:105], 0
	v_mov_b64_e32 v[106:107], 0
	v_mov_b64_e32 v[108:109], 0
	v_mov_b64_e32 v[110:111], 0
	v_mov_b64_e32 v[112:113], 0
	v_mov_b64_e32 v[114:115], 0
	v_mov_b64_e32 v[116:117], 0
	v_mov_b64_e32 v[118:119], 0
	v_mov_b64_e32 v[120:121], 0
	v_mov_b64_e32 v[122:123], 0
	v_mov_b64_e32 v[124:125], 0
	v_mov_b64_e32 v[126:127], 0
	s_branch .LBB0_382

.LBB0_593:
	ds_read_b128 v[148:151], v204 offset:32768
	ds_read_b128 v[144:147], v204 offset:36864
	ds_read_b128 v[140:143], v204 offset:40960
	ds_read_b128 v[136:139], v204 offset:45056
	ds_read_b128 v[132:135], v205
	ds_read_b128 v[128:131], v205 offset:4096
	s_mov_b32 s66, -2
	v_mov_b64_e32 v[0:1], 0
	v_mov_b64_e32 v[2:3], 0
	v_mov_b64_e32 v[4:5], 0
	v_mov_b64_e32 v[6:7], 0
	v_mov_b64_e32 v[8:9], 0
	v_mov_b64_e32 v[10:11], 0
	v_mov_b64_e32 v[12:13], 0
	v_mov_b64_e32 v[14:15], 0
	v_mov_b64_e32 v[16:17], 0
	v_mov_b64_e32 v[18:19], 0
	v_mov_b64_e32 v[20:21], 0
	v_mov_b64_e32 v[22:23], 0
	v_mov_b64_e32 v[24:25], 0
	v_mov_b64_e32 v[26:27], 0
	v_mov_b64_e32 v[28:29], 0
	v_mov_b64_e32 v[30:31], 0
	v_mov_b64_e32 v[32:33], 0
	v_mov_b64_e32 v[34:35], 0
	v_mov_b64_e32 v[36:37], 0
	v_mov_b64_e32 v[38:39], 0
	v_mov_b64_e32 v[40:41], 0
	v_mov_b64_e32 v[42:43], 0
	v_mov_b64_e32 v[44:45], 0
	v_mov_b64_e32 v[46:47], 0
	v_mov_b64_e32 v[48:49], 0
	v_mov_b64_e32 v[50:51], 0
	v_mov_b64_e32 v[52:53], 0
	v_mov_b64_e32 v[54:55], 0
	v_mov_b64_e32 v[56:57], 0
	v_mov_b64_e32 v[58:59], 0
	v_mov_b64_e32 v[60:61], 0
	v_mov_b64_e32 v[62:63], 0
	v_mov_b64_e32 v[64:65], 0
	v_mov_b64_e32 v[66:67], 0
	v_mov_b64_e32 v[68:69], 0
	v_mov_b64_e32 v[70:71], 0
	v_mov_b64_e32 v[72:73], 0
	v_mov_b64_e32 v[74:75], 0
	v_mov_b64_e32 v[76:77], 0
	v_mov_b64_e32 v[78:79], 0
	v_mov_b64_e32 v[80:81], 0
	v_mov_b64_e32 v[82:83], 0
	v_mov_b64_e32 v[84:85], 0
	v_mov_b64_e32 v[86:87], 0
	v_mov_b64_e32 v[88:89], 0
	v_mov_b64_e32 v[90:91], 0
	v_mov_b64_e32 v[92:93], 0
	v_mov_b64_e32 v[94:95], 0
	v_mov_b64_e32 v[96:97], 0
	v_mov_b64_e32 v[98:99], 0
	v_mov_b64_e32 v[100:101], 0
	v_mov_b64_e32 v[102:103], 0
	v_mov_b64_e32 v[104:105], 0
	v_mov_b64_e32 v[106:107], 0
	v_mov_b64_e32 v[108:109], 0
	v_mov_b64_e32 v[110:111], 0
	v_mov_b64_e32 v[112:113], 0
	v_mov_b64_e32 v[114:115], 0
	v_mov_b64_e32 v[116:117], 0
	v_mov_b64_e32 v[118:119], 0
	v_mov_b64_e32 v[120:121], 0
	v_mov_b64_e32 v[122:123], 0
	v_mov_b64_e32 v[124:125], 0
	v_mov_b64_e32 v[126:127], 0
	s_branch .LBB0_596

.LBB0_733:
	ds_read_b128 v[148:151], v205 offset:32768
	ds_read_b128 v[144:147], v205 offset:36864
	ds_read_b128 v[140:143], v205 offset:40960
	ds_read_b128 v[136:139], v205 offset:45056
	ds_read_b128 v[132:135], v206
	ds_read_b128 v[128:131], v206 offset:4096
	s_mov_b32 s52, s79
	s_mov_b32 s24, s31
	s_mov_b32 s53, -2
	v_mov_b64_e32 v[0:1], 0
	v_mov_b64_e32 v[2:3], 0
	v_mov_b64_e32 v[4:5], 0
	v_mov_b64_e32 v[6:7], 0
	v_mov_b64_e32 v[8:9], 0
	v_mov_b64_e32 v[10:11], 0
	v_mov_b64_e32 v[12:13], 0
	v_mov_b64_e32 v[14:15], 0
	v_mov_b64_e32 v[16:17], 0
	v_mov_b64_e32 v[18:19], 0
	v_mov_b64_e32 v[20:21], 0
	v_mov_b64_e32 v[22:23], 0
	v_mov_b64_e32 v[24:25], 0
	v_mov_b64_e32 v[26:27], 0
	v_mov_b64_e32 v[28:29], 0
	v_mov_b64_e32 v[30:31], 0
	v_mov_b64_e32 v[32:33], 0
	v_mov_b64_e32 v[34:35], 0
	v_mov_b64_e32 v[36:37], 0
	v_mov_b64_e32 v[38:39], 0
	v_mov_b64_e32 v[40:41], 0
	v_mov_b64_e32 v[42:43], 0
	v_mov_b64_e32 v[44:45], 0
	v_mov_b64_e32 v[46:47], 0
	v_mov_b64_e32 v[48:49], 0
	v_mov_b64_e32 v[50:51], 0
	v_mov_b64_e32 v[52:53], 0
	v_mov_b64_e32 v[54:55], 0
	v_mov_b64_e32 v[56:57], 0
	v_mov_b64_e32 v[58:59], 0
	v_mov_b64_e32 v[60:61], 0
	v_mov_b64_e32 v[62:63], 0
	v_mov_b64_e32 v[64:65], 0
	v_mov_b64_e32 v[66:67], 0
	v_mov_b64_e32 v[68:69], 0
	v_mov_b64_e32 v[70:71], 0
	v_mov_b64_e32 v[72:73], 0
	v_mov_b64_e32 v[74:75], 0
	v_mov_b64_e32 v[76:77], 0
	v_mov_b64_e32 v[78:79], 0
	v_mov_b64_e32 v[80:81], 0
	v_mov_b64_e32 v[82:83], 0
	v_mov_b64_e32 v[84:85], 0
	v_mov_b64_e32 v[86:87], 0
	v_mov_b64_e32 v[88:89], 0
	v_mov_b64_e32 v[90:91], 0
	v_mov_b64_e32 v[92:93], 0
	v_mov_b64_e32 v[94:95], 0
	v_mov_b64_e32 v[96:97], 0
	v_mov_b64_e32 v[98:99], 0
	v_mov_b64_e32 v[100:101], 0
	v_mov_b64_e32 v[102:103], 0
	v_mov_b64_e32 v[104:105], 0
	v_mov_b64_e32 v[106:107], 0
	v_mov_b64_e32 v[108:109], 0
	v_mov_b64_e32 v[110:111], 0
	v_mov_b64_e32 v[112:113], 0
	v_mov_b64_e32 v[114:115], 0
	v_mov_b64_e32 v[116:117], 0
	v_mov_b64_e32 v[118:119], 0
	v_mov_b64_e32 v[120:121], 0
	v_mov_b64_e32 v[122:123], 0
	v_mov_b64_e32 v[124:125], 0
	v_mov_b64_e32 v[126:127], 0
	s_branch .LBB0_736

.LBB0_947:
	ds_read_b128 v[148:151], v206 offset:32768
	ds_read_b128 v[144:147], v206 offset:36864
	ds_read_b128 v[140:143], v206 offset:40960
	ds_read_b128 v[136:139], v206 offset:45056
	ds_read_b128 v[132:135], v207
	ds_read_b128 v[128:131], v207 offset:4096
	s_mov_b32 s30, s80
	s_mov_b32 s31, s25
	s_mov_b32 s80, -2
	v_mov_b64_e32 v[0:1], 0
	v_mov_b64_e32 v[2:3], 0
	v_mov_b64_e32 v[4:5], 0
	v_mov_b64_e32 v[6:7], 0
	v_mov_b64_e32 v[8:9], 0
	v_mov_b64_e32 v[10:11], 0
	v_mov_b64_e32 v[12:13], 0
	v_mov_b64_e32 v[14:15], 0
	v_mov_b64_e32 v[16:17], 0
	v_mov_b64_e32 v[18:19], 0
	v_mov_b64_e32 v[20:21], 0
	v_mov_b64_e32 v[22:23], 0
	v_mov_b64_e32 v[24:25], 0
	v_mov_b64_e32 v[26:27], 0
	v_mov_b64_e32 v[28:29], 0
	v_mov_b64_e32 v[30:31], 0
	v_mov_b64_e32 v[32:33], 0
	v_mov_b64_e32 v[34:35], 0
	v_mov_b64_e32 v[36:37], 0
	v_mov_b64_e32 v[38:39], 0
	v_mov_b64_e32 v[40:41], 0
	v_mov_b64_e32 v[42:43], 0
	v_mov_b64_e32 v[44:45], 0
	v_mov_b64_e32 v[46:47], 0
	v_mov_b64_e32 v[48:49], 0
	v_mov_b64_e32 v[50:51], 0
	v_mov_b64_e32 v[52:53], 0
	v_mov_b64_e32 v[54:55], 0
	v_mov_b64_e32 v[56:57], 0
	v_mov_b64_e32 v[58:59], 0
	v_mov_b64_e32 v[60:61], 0
	v_mov_b64_e32 v[62:63], 0
	v_mov_b64_e32 v[64:65], 0
	v_mov_b64_e32 v[66:67], 0
	v_mov_b64_e32 v[68:69], 0
	v_mov_b64_e32 v[70:71], 0
	v_mov_b64_e32 v[72:73], 0
	v_mov_b64_e32 v[74:75], 0
	v_mov_b64_e32 v[76:77], 0
	v_mov_b64_e32 v[78:79], 0
	v_mov_b64_e32 v[80:81], 0
	v_mov_b64_e32 v[82:83], 0
	v_mov_b64_e32 v[84:85], 0
	v_mov_b64_e32 v[86:87], 0
	v_mov_b64_e32 v[88:89], 0
	v_mov_b64_e32 v[90:91], 0
	v_mov_b64_e32 v[92:93], 0
	v_mov_b64_e32 v[94:95], 0
	v_mov_b64_e32 v[96:97], 0
	v_mov_b64_e32 v[98:99], 0
	v_mov_b64_e32 v[100:101], 0
	v_mov_b64_e32 v[102:103], 0
	v_mov_b64_e32 v[104:105], 0
	v_mov_b64_e32 v[106:107], 0
	v_mov_b64_e32 v[108:109], 0
	v_mov_b64_e32 v[110:111], 0
	v_mov_b64_e32 v[112:113], 0
	v_mov_b64_e32 v[114:115], 0
	v_mov_b64_e32 v[116:117], 0
	v_mov_b64_e32 v[118:119], 0
	v_mov_b64_e32 v[120:121], 0
	v_mov_b64_e32 v[122:123], 0
	v_mov_b64_e32 v[124:125], 0
	v_mov_b64_e32 v[126:127], 0
	s_branch .LBB0_951

.LBB0_1201:
	ds_read_b128 v[148:151], v204 offset:32768
	ds_read_b128 v[144:147], v204 offset:36864
	ds_read_b128 v[140:143], v204 offset:40960
	ds_read_b128 v[136:139], v204 offset:45056
	ds_read_b128 v[132:135], v205
	ds_read_b128 v[128:131], v205 offset:4096
	s_mov_b32 s48, s30
	s_mov_b32 s24, s43
	s_mov_b32 s49, -2
	v_mov_b64_e32 v[0:1], 0
	v_mov_b64_e32 v[2:3], 0
	v_mov_b64_e32 v[4:5], 0
	v_mov_b64_e32 v[6:7], 0
	v_mov_b64_e32 v[8:9], 0
	v_mov_b64_e32 v[10:11], 0
	v_mov_b64_e32 v[12:13], 0
	v_mov_b64_e32 v[14:15], 0
	v_mov_b64_e32 v[16:17], 0
	v_mov_b64_e32 v[18:19], 0
	v_mov_b64_e32 v[20:21], 0
	v_mov_b64_e32 v[22:23], 0
	v_mov_b64_e32 v[24:25], 0
	v_mov_b64_e32 v[26:27], 0
	v_mov_b64_e32 v[28:29], 0
	v_mov_b64_e32 v[30:31], 0
	v_mov_b64_e32 v[32:33], 0
	v_mov_b64_e32 v[34:35], 0
	v_mov_b64_e32 v[36:37], 0
	v_mov_b64_e32 v[38:39], 0
	v_mov_b64_e32 v[40:41], 0
	v_mov_b64_e32 v[42:43], 0
	v_mov_b64_e32 v[44:45], 0
	v_mov_b64_e32 v[46:47], 0
	v_mov_b64_e32 v[48:49], 0
	v_mov_b64_e32 v[50:51], 0
	v_mov_b64_e32 v[52:53], 0
	v_mov_b64_e32 v[54:55], 0
	v_mov_b64_e32 v[56:57], 0
	v_mov_b64_e32 v[58:59], 0
	v_mov_b64_e32 v[60:61], 0
	v_mov_b64_e32 v[62:63], 0
	v_mov_b64_e32 v[64:65], 0
	v_mov_b64_e32 v[66:67], 0
	v_mov_b64_e32 v[68:69], 0
	v_mov_b64_e32 v[70:71], 0
	v_mov_b64_e32 v[72:73], 0
	v_mov_b64_e32 v[74:75], 0
	v_mov_b64_e32 v[76:77], 0
	v_mov_b64_e32 v[78:79], 0
	v_mov_b64_e32 v[80:81], 0
	v_mov_b64_e32 v[82:83], 0
	v_mov_b64_e32 v[84:85], 0
	v_mov_b64_e32 v[86:87], 0
	v_mov_b64_e32 v[88:89], 0
	v_mov_b64_e32 v[90:91], 0
	v_mov_b64_e32 v[92:93], 0
	v_mov_b64_e32 v[94:95], 0
	v_mov_b64_e32 v[96:97], 0
	v_mov_b64_e32 v[98:99], 0
	v_mov_b64_e32 v[100:101], 0
	v_mov_b64_e32 v[102:103], 0
	v_mov_b64_e32 v[104:105], 0
	v_mov_b64_e32 v[106:107], 0
	v_mov_b64_e32 v[108:109], 0
	v_mov_b64_e32 v[110:111], 0
	v_mov_b64_e32 v[112:113], 0
	v_mov_b64_e32 v[114:115], 0
	v_mov_b64_e32 v[116:117], 0
	v_mov_b64_e32 v[118:119], 0
	v_mov_b64_e32 v[120:121], 0
	v_mov_b64_e32 v[122:123], 0
	v_mov_b64_e32 v[124:125], 0
	v_mov_b64_e32 v[126:127], 0
	s_branch .LBB0_1204

.LBB0_1520:
	ds_read_b128 v[148:151], v204 offset:32768
	ds_read_b128 v[144:147], v204 offset:36864
	ds_read_b128 v[140:143], v204 offset:40960
	ds_read_b128 v[136:139], v204 offset:45056
	ds_read_b128 v[132:135], v205
	ds_read_b128 v[128:131], v205 offset:4096
	s_mov_b32 s42, s22
	s_mov_b32 s18, s41
	s_mov_b32 s43, -2
	v_mov_b64_e32 v[0:1], 0
	v_mov_b64_e32 v[2:3], 0
	v_mov_b64_e32 v[4:5], 0
	v_mov_b64_e32 v[6:7], 0
	v_mov_b64_e32 v[8:9], 0
	v_mov_b64_e32 v[10:11], 0
	v_mov_b64_e32 v[12:13], 0
	v_mov_b64_e32 v[14:15], 0
	v_mov_b64_e32 v[16:17], 0
	v_mov_b64_e32 v[18:19], 0
	v_mov_b64_e32 v[20:21], 0
	v_mov_b64_e32 v[22:23], 0
	v_mov_b64_e32 v[24:25], 0
	v_mov_b64_e32 v[26:27], 0
	v_mov_b64_e32 v[28:29], 0
	v_mov_b64_e32 v[30:31], 0
	v_mov_b64_e32 v[32:33], 0
	v_mov_b64_e32 v[34:35], 0
	v_mov_b64_e32 v[36:37], 0
	v_mov_b64_e32 v[38:39], 0
	v_mov_b64_e32 v[40:41], 0
	v_mov_b64_e32 v[42:43], 0
	v_mov_b64_e32 v[44:45], 0
	v_mov_b64_e32 v[46:47], 0
	v_mov_b64_e32 v[48:49], 0
	v_mov_b64_e32 v[50:51], 0
	v_mov_b64_e32 v[52:53], 0
	v_mov_b64_e32 v[54:55], 0
	v_mov_b64_e32 v[56:57], 0
	v_mov_b64_e32 v[58:59], 0
	v_mov_b64_e32 v[60:61], 0
	v_mov_b64_e32 v[62:63], 0
	v_mov_b64_e32 v[64:65], 0
	v_mov_b64_e32 v[66:67], 0
	v_mov_b64_e32 v[68:69], 0
	v_mov_b64_e32 v[70:71], 0
	v_mov_b64_e32 v[72:73], 0
	v_mov_b64_e32 v[74:75], 0
	v_mov_b64_e32 v[76:77], 0
	v_mov_b64_e32 v[78:79], 0
	v_mov_b64_e32 v[80:81], 0
	v_mov_b64_e32 v[82:83], 0
	v_mov_b64_e32 v[84:85], 0
	v_mov_b64_e32 v[86:87], 0
	v_mov_b64_e32 v[88:89], 0
	v_mov_b64_e32 v[90:91], 0
	v_mov_b64_e32 v[92:93], 0
	v_mov_b64_e32 v[94:95], 0
	v_mov_b64_e32 v[96:97], 0
	v_mov_b64_e32 v[98:99], 0
	v_mov_b64_e32 v[100:101], 0
	v_mov_b64_e32 v[102:103], 0
	v_mov_b64_e32 v[104:105], 0
	v_mov_b64_e32 v[106:107], 0
	v_mov_b64_e32 v[108:109], 0
	v_mov_b64_e32 v[110:111], 0
	v_mov_b64_e32 v[112:113], 0
	v_mov_b64_e32 v[114:115], 0
	v_mov_b64_e32 v[116:117], 0
	v_mov_b64_e32 v[118:119], 0
	v_mov_b64_e32 v[120:121], 0
	v_mov_b64_e32 v[122:123], 0
	v_mov_b64_e32 v[124:125], 0
	v_mov_b64_e32 v[126:127], 0
	s_branch .LBB0_1523
